# GLU weight loads batched in s5_out; hg_local V^T staging loads batched
# speedup vs baseline: 1.2105x; 1.0063x over previous
.LBB0_874:
	v_and_b32_e32 v0, 0xffffffe0, v80
	v_ashrrev_i32_e32 v1, 31, v0
	v_and_b32_e32 v3, 0xc0, v79
	v_lshlrev_b64 v[4:5], 13, v[0:1]
	v_lshl_add_u64 v[4:5], v[70:71], 0, v[4:5]
	v_lshlrev_b32_e32 v228, 2, v3
	v_lshl_add_u64 v[4:5], v[4:5], 0, v[228:229]
	v_mov_b32_e32 v75, v229
	v_lshl_add_u64 v[4:5], v[4:5], 0, v[74:75]
	v_add_co_u32_e32 v4, vcc, s1, v4
	v_readlane_b32 s2, v255, 25
	s_nop 0
	v_addc_co_u32_e32 v5, vcc, 0, v5, vcc
	v_bfe_u32 v18, v64, 2, 1
	v_readlane_b32 s3, v255, 26
	s_mov_b64 s[0:1], 0x2000
	global_load_dword v120, v[4:5], off
	v_lshl_add_u64 v[4:5], v[4:5], 0, s[0:1]
	global_load_dword v121, v[4:5], off
	v_lshl_add_u64 v[4:5], v[4:5], 0, s[0:1]
	global_load_dword v122, v[4:5], off
	v_lshl_add_u64 v[4:5], v[4:5], 0, s[0:1]
	global_load_dword v123, v[4:5], off
	v_lshl_add_u64 v[4:5], v[4:5], 0, s[0:1]
	global_load_dword v124, v[4:5], off
	v_lshl_add_u64 v[4:5], v[4:5], 0, s[0:1]
	global_load_dword v125, v[4:5], off
	v_lshl_add_u64 v[4:5], v[4:5], 0, s[0:1]
	global_load_dword v126, v[4:5], off
	v_lshl_add_u64 v[4:5], v[4:5], 0, s[0:1]
	global_load_dword v127, v[4:5], off
	v_lshl_add_u64 v[4:5], v[4:5], 0, s[0:1]
	global_load_dword v128, v[4:5], off
	v_lshl_add_u64 v[4:5], v[4:5], 0, s[0:1]
	global_load_dword v129, v[4:5], off
	v_lshl_add_u64 v[4:5], v[4:5], 0, s[0:1]
	global_load_dword v130, v[4:5], off
	v_lshl_add_u64 v[4:5], v[4:5], 0, s[0:1]
	global_load_dword v131, v[4:5], off
	v_lshl_add_u64 v[4:5], v[4:5], 0, s[0:1]
	global_load_dword v132, v[4:5], off
	v_lshl_add_u64 v[4:5], v[4:5], 0, s[0:1]
	global_load_dword v133, v[4:5], off
	v_lshl_add_u64 v[4:5], v[4:5], 0, s[0:1]
	global_load_dword v134, v[4:5], off
	v_lshl_add_u64 v[4:5], v[4:5], 0, s[0:1]
	global_load_dword v135, v[4:5], off
	v_lshl_add_u64 v[4:5], v[4:5], 0, s[0:1]
	global_load_dword v136, v[4:5], off
	v_lshl_add_u64 v[4:5], v[4:5], 0, s[0:1]
	global_load_dword v137, v[4:5], off
	v_lshl_add_u64 v[4:5], v[4:5], 0, s[0:1]
	global_load_dword v138, v[4:5], off
	v_lshl_add_u64 v[4:5], v[4:5], 0, s[0:1]
	global_load_dword v139, v[4:5], off
	v_lshl_add_u64 v[4:5], v[4:5], 0, s[0:1]
	global_load_dword v140, v[4:5], off
	v_lshl_add_u64 v[4:5], v[4:5], 0, s[0:1]
	global_load_dword v141, v[4:5], off
	v_lshl_add_u64 v[4:5], v[4:5], 0, s[0:1]
	global_load_dword v142, v[4:5], off
	v_lshl_add_u64 v[4:5], v[4:5], 0, s[0:1]
	global_load_dword v143, v[4:5], off
	v_lshl_add_u64 v[4:5], v[4:5], 0, s[0:1]
	global_load_dword v144, v[4:5], off
	v_lshl_add_u64 v[4:5], v[4:5], 0, s[0:1]
	global_load_dword v145, v[4:5], off
	v_lshl_add_u64 v[4:5], v[4:5], 0, s[0:1]
	global_load_dword v146, v[4:5], off
	v_lshl_add_u64 v[4:5], v[4:5], 0, s[0:1]
	global_load_dword v147, v[4:5], off
	v_lshl_add_u64 v[4:5], v[4:5], 0, s[0:1]
	global_load_dword v148, v[4:5], off
	v_lshl_add_u64 v[4:5], v[4:5], 0, s[0:1]
	global_load_dword v149, v[4:5], off
	v_lshl_add_u64 v[4:5], v[4:5], 0, s[0:1]
	global_load_dword v150, v[4:5], off
	v_lshl_add_u64 v[4:5], v[4:5], 0, s[0:1]
	global_load_dword v151, v[4:5], off
	s_mov_b64 s[0:1], -1
	s_and_b64 vcc, exec, s[2:3]
	s_waitcnt vmcnt(24)
	v_bfe_u32 v1, v120, 16, 1
	v_bfe_u32 v2, v121, 16, 1
	v_add3_u32 v1, v120, v1, s89
	v_add3_u32 v2, v121, v2, s89
	v_lshrrev_b32_e32 v1, 16, v1
	v_and_or_b32 v4, v2, s75, v1
	v_bfe_u32 v1, v122, 16, 1
	v_bfe_u32 v2, v123, 16, 1
	v_add3_u32 v1, v122, v1, s89
	v_add3_u32 v2, v123, v2, s89
	v_lshrrev_b32_e32 v1, 16, v1
	v_and_or_b32 v5, v2, s75, v1
	v_bfe_u32 v1, v124, 16, 1
	v_bfe_u32 v2, v125, 16, 1
	v_add3_u32 v1, v124, v1, s89
	v_add3_u32 v2, v125, v2, s89
	v_lshrrev_b32_e32 v1, 16, v1
	v_and_or_b32 v6, v2, s75, v1
	v_bfe_u32 v1, v126, 16, 1
	v_bfe_u32 v2, v127, 16, 1
	v_add3_u32 v1, v126, v1, s89
	v_add3_u32 v2, v127, v2, s89
	v_lshrrev_b32_e32 v1, 16, v1
	v_and_or_b32 v7, v2, s75, v1
	ds_write_b128 v67, v[4:7]
	s_waitcnt vmcnt(16)
	v_bfe_u32 v1, v128, 16, 1
	v_bfe_u32 v2, v129, 16, 1
	v_add3_u32 v1, v128, v1, s89
	v_add3_u32 v2, v129, v2, s89
	v_lshrrev_b32_e32 v1, 16, v1
	v_and_or_b32 v4, v2, s75, v1
	v_bfe_u32 v1, v130, 16, 1
	v_bfe_u32 v2, v131, 16, 1
	v_add3_u32 v1, v130, v1, s89
	v_add3_u32 v2, v131, v2, s89
	v_lshrrev_b32_e32 v1, 16, v1
	v_and_or_b32 v5, v2, s75, v1
	v_bfe_u32 v1, v132, 16, 1
	v_bfe_u32 v2, v133, 16, 1
	v_add3_u32 v1, v132, v1, s89
	v_add3_u32 v2, v133, v2, s89
	v_lshrrev_b32_e32 v1, 16, v1
	v_and_or_b32 v6, v2, s75, v1
	v_bfe_u32 v1, v134, 16, 1
	v_bfe_u32 v2, v135, 16, 1
	v_add3_u32 v1, v134, v1, s89
	v_add3_u32 v2, v135, v2, s89
	v_lshrrev_b32_e32 v1, 16, v1
	v_and_or_b32 v7, v2, s75, v1
	ds_write_b128 v67, v[4:7] offset:16
	s_waitcnt vmcnt(8)
	v_bfe_u32 v1, v136, 16, 1
	v_bfe_u32 v2, v137, 16, 1
	v_add3_u32 v1, v136, v1, s89
	v_add3_u32 v2, v137, v2, s89
	v_lshrrev_b32_e32 v1, 16, v1
	v_and_or_b32 v4, v2, s75, v1
	v_bfe_u32 v1, v138, 16, 1
	v_bfe_u32 v2, v139, 16, 1
	v_add3_u32 v1, v138, v1, s89
	v_add3_u32 v2, v139, v2, s89
	v_lshrrev_b32_e32 v1, 16, v1
	v_and_or_b32 v5, v2, s75, v1
	v_bfe_u32 v1, v140, 16, 1
	v_bfe_u32 v2, v141, 16, 1
	v_add3_u32 v1, v140, v1, s89
	v_add3_u32 v2, v141, v2, s89
	v_lshrrev_b32_e32 v1, 16, v1
	v_and_or_b32 v6, v2, s75, v1
	v_bfe_u32 v1, v142, 16, 1
	v_bfe_u32 v2, v143, 16, 1
	v_add3_u32 v1, v142, v1, s89
	v_add3_u32 v2, v143, v2, s89
	v_lshrrev_b32_e32 v1, 16, v1
	v_and_or_b32 v7, v2, s75, v1
	ds_write_b128 v67, v[4:7] offset:32
	s_waitcnt vmcnt(0)
	v_bfe_u32 v1, v144, 16, 1
	v_bfe_u32 v2, v145, 16, 1
	v_add3_u32 v1, v144, v1, s89
	v_add3_u32 v2, v145, v2, s89
	v_lshrrev_b32_e32 v1, 16, v1
	v_and_or_b32 v4, v2, s75, v1
	v_bfe_u32 v1, v146, 16, 1
	v_bfe_u32 v2, v147, 16, 1
	v_add3_u32 v1, v146, v1, s89
	v_add3_u32 v2, v147, v2, s89
	v_lshrrev_b32_e32 v1, 16, v1
	v_and_or_b32 v5, v2, s75, v1
	v_bfe_u32 v1, v148, 16, 1
	v_bfe_u32 v2, v149, 16, 1
	v_add3_u32 v1, v148, v1, s89
	v_add3_u32 v2, v149, v2, s89
	v_lshrrev_b32_e32 v1, 16, v1
	v_and_or_b32 v6, v2, s75, v1
	v_bfe_u32 v1, v150, 16, 1
	v_bfe_u32 v2, v151, 16, 1
	v_add3_u32 v1, v150, v1, s89
	v_add3_u32 v2, v151, v2, s89
	v_lshrrev_b32_e32 v1, 16, v1
	v_and_or_b32 v7, v2, s75, v1
	ds_write_b128 v67, v[4:7] offset:48
	v_lshlrev_b32_e32 v1, 8, v18
	s_cbranch_vccz .LBB0_876
	ds_read_b64 v[4:5], v229 offset:63656
	v_lshlrev_b32_e32 v2, 8, v18
	v_or3_b32 v3, v3, v66, v2
	v_mov_b32_e32 v7, v229
	v_lshlrev_b32_e32 v6, 2, v3
	s_waitcnt lgkmcnt(0)
	v_lshl_add_u64 v[4:5], v[4:5], 0, v[6:7]
	flat_load_dword v3, v[4:5]
	s_nop 0
	flat_load_dword v4, v[4:5] offset:2048
	s_mov_b32 s0, 0x3fb8aa3b
	s_waitcnt vmcnt(0) lgkmcnt(0)
	v_sub_f32_e32 v3, v3, v4
	v_mul_f32_e32 v4, 0x3fb8aa3b, v3
	v_fma_f32 v5, v3, s0, -v4
	v_rndne_f32_e32 v6, v4
	v_fmac_f32_e32 v5, 0x32a5705f, v3
	v_sub_f32_e32 v4, v4, v6
	v_add_f32_e32 v4, v4, v5
	v_cvt_i32_f32_e32 v6, v6
	v_exp_f32_e32 v4, v4
	s_mov_b32 s0, 0xc2ce8ed0
	v_cmp_ngt_f32_e32 vcc, s0, v3
	s_mov_b32 s0, 0x42b17218
	v_ldexp_f32 v4, v4, v6
	v_cndmask_b32_e32 v4, 0, v4, vcc
	v_cmp_nlt_f32_e32 vcc, s0, v3
	s_nop 1
	v_cndmask_b32_e32 v3, v248, v4, vcc
	v_add_f32_e32 v3, 1.0, v3
	v_div_scale_f32 v4, s[0:1], v3, v3, 1.0
	v_rcp_f32_e32 v5, v4
	v_div_scale_f32 v6, vcc, 1.0, v3, 1.0
	s_mov_b64 s[0:1], 0
	v_fma_f32 v7, -v4, v5, 1.0
	v_fmac_f32_e32 v5, v7, v5
	v_mul_f32_e32 v7, v6, v5
	v_fma_f32 v8, -v4, v7, v6
	v_fmac_f32_e32 v7, v8, v5
	v_fma_f32 v4, -v4, v7, v6
	v_div_fmas_f32 v4, v4, v5, v7
	v_div_fixup_f32 v7, v4, v3, 1.0

.LBB0_1160:
	v_lshl_add_u64 v[44:45], v[38:39], 0, s[0:1]
	v_add_co_u32_e32 v56, vcc, s27, v44
	s_nop 1
	v_addc_co_u32_e32 v57, vcc, 0, v45, vcc
	v_lshl_add_u64 v[44:45], v[36:37], 0, s[0:1]
	v_add_co_u32_e32 v58, vcc, s27, v44
	s_nop 1
	v_addc_co_u32_e32 v59, vcc, 0, v45, vcc
	global_load_dwordx4 v[140:143], v[56:57], off
	global_load_dwordx4 v[144:147], v[58:59], off
	global_load_dwordx4 v[148:151], v[56:57], off offset:32
	global_load_dwordx4 v[152:155], v[58:59], off offset:32
	global_load_dwordx4 v[156:159], v[56:57], off offset:64
	global_load_dwordx4 v[160:163], v[58:59], off offset:64
	global_load_dwordx4 v[164:167], v[56:57], off offset:96
	global_load_dwordx4 v[168:171], v[58:59], off offset:96
	global_load_dwordx4 v[172:175], v[56:57], off offset:128
	global_load_dwordx4 v[176:179], v[58:59], off offset:128
	global_load_dwordx4 v[180:183], v[56:57], off offset:160
	global_load_dwordx4 v[184:187], v[58:59], off offset:160
	global_load_dwordx4 v[188:191], v[56:57], off offset:192
	global_load_dwordx4 v[192:195], v[58:59], off offset:192
	global_load_dwordx4 v[196:199], v[56:57], off offset:224
	global_load_dwordx4 v[200:203], v[58:59], off offset:224
	ds_read_b128 v[66:69], v41
	ds_read_b128 v[70:73], v41 offset:32
	ds_read_b128 v[74:77], v41 offset:64
	ds_read_b128 v[78:81], v41 offset:96
	ds_read_b128 v[82:85], v41 offset:128
	ds_read_b128 v[86:89], v41 offset:160
	ds_read_b128 v[90:93], v41 offset:192
	ds_read_b128 v[94:97], v41 offset:224
	v_add_u32_e32 v41, 0x100, v41
	s_add_u32 s0, s0, 0x100
	s_addc_u32 s1, s1, 0
	s_waitcnt vmcnt(14) lgkmcnt(7)
	v_mfma_f32_32x32x16_bf16 v[16:31], v[66:69], v[140:143], v[16:31]
	v_mfma_f32_32x32x16_bf16 v[0:15], v[66:69], v[144:147], v[0:15]
	s_waitcnt vmcnt(12) lgkmcnt(6)
	v_mfma_f32_32x32x16_bf16 v[16:31], v[70:73], v[148:151], v[16:31]
	v_mfma_f32_32x32x16_bf16 v[0:15], v[70:73], v[152:155], v[0:15]
	s_waitcnt vmcnt(10) lgkmcnt(5)
	v_mfma_f32_32x32x16_bf16 v[16:31], v[74:77], v[156:159], v[16:31]
	v_mfma_f32_32x32x16_bf16 v[0:15], v[74:77], v[160:163], v[0:15]
	s_waitcnt vmcnt(8) lgkmcnt(4)
	v_mfma_f32_32x32x16_bf16 v[16:31], v[78:81], v[164:167], v[16:31]
	v_mfma_f32_32x32x16_bf16 v[0:15], v[78:81], v[168:171], v[0:15]
	s_waitcnt vmcnt(6) lgkmcnt(3)
	v_mfma_f32_32x32x16_bf16 v[16:31], v[82:85], v[172:175], v[16:31]
	v_mfma_f32_32x32x16_bf16 v[0:15], v[82:85], v[176:179], v[0:15]
	s_waitcnt vmcnt(4) lgkmcnt(2)
	v_mfma_f32_32x32x16_bf16 v[16:31], v[86:89], v[180:183], v[16:31]
	v_mfma_f32_32x32x16_bf16 v[0:15], v[86:89], v[184:187], v[0:15]
	s_waitcnt vmcnt(2) lgkmcnt(1)
	v_mfma_f32_32x32x16_bf16 v[16:31], v[90:93], v[188:191], v[16:31]
	v_mfma_f32_32x32x16_bf16 v[0:15], v[90:93], v[192:195], v[0:15]
	s_waitcnt vmcnt(0) lgkmcnt(0)
	v_mfma_f32_32x32x16_bf16 v[16:31], v[94:97], v[196:199], v[16:31]
	v_mfma_f32_32x32x16_bf16 v[0:15], v[94:97], v[200:203], v[0:15]
	s_cmpk_eq_i32 s0, 0x200
	s_cbranch_scc0 .LBB0_1160
	s_nop 7
	v_mul_f32_e32 v16, 0xbfb8aa3b, v16
	v_lshlrev_b32_e32 v36, 1, v40
	v_exp_f32_e32 v16, v16
	v_mul_f32_e32 v0, 0xbfb8aa3b, v0
	v_lshl_add_u32 v37, v64, 1, v36
	v_exp_f32_e32 v0, v0
	v_mad_u32_u24 v38, v42, s24, v37
	ds_read_u16 v39, v38 offset:34816
	v_add_f32_e32 v16, 1.0, v16
	ds_read_u16 v38, v38 offset:34880
	v_rcp_f32_e32 v16, v16
	v_add_f32_e32 v0, 1.0, v0
	v_rcp_f32_e32 v0, v0
	s_waitcnt lgkmcnt(1)
	v_lshlrev_b32_e32 v39, 16, v39
	v_and_b32_e32 v36, 64, v244
	v_mul_f32_e32 v67, v16, v39
	s_waitcnt lgkmcnt(0)
	v_lshlrev_b32_e32 v16, 16, v38
	v_add_u32_e32 v36, 64, v36
	v_mul_f32_e32 v66, v0, v16
	v_xor_b32_e32 v16, 16, v244
	v_cmp_lt_i32_e32 vcc, v16, v36
	v_mul_f32_e32 v0, v66, v66
	v_fmac_f32_e32 v0, v67, v67
	v_cndmask_b32_e32 v16, v244, v16, vcc
	v_lshlrev_b32_e32 v16, 2, v16
	ds_bpermute_b32 v38, v16, v0
	s_waitcnt lgkmcnt(0)
	v_add_f32_e32 v0, v0, v38
	v_xor_b32_e32 v38, 8, v244
	v_cmp_lt_i32_e32 vcc, v38, v36
	s_nop 1
	v_cndmask_b32_e32 v38, v244, v38, vcc
	v_lshlrev_b32_e32 v41, 2, v38
	ds_bpermute_b32 v38, v41, v0
	s_waitcnt lgkmcnt(0)
	v_add_f32_e32 v0, v0, v38
	v_xor_b32_e32 v38, 4, v244
	v_cmp_lt_i32_e32 vcc, v38, v36
	s_nop 1
	v_cndmask_b32_e32 v38, v244, v38, vcc
	v_lshlrev_b32_e32 v52, 2, v38
	ds_bpermute_b32 v38, v52, v0
	s_waitcnt lgkmcnt(0)
	v_add_f32_e32 v0, v0, v38
	v_xor_b32_e32 v38, 2, v244
	v_cmp_lt_i32_e32 vcc, v38, v36
	s_nop 1
	v_cndmask_b32_e32 v38, v244, v38, vcc
	v_lshlrev_b32_e32 v68, 2, v38
	ds_bpermute_b32 v38, v68, v0
	s_waitcnt lgkmcnt(0)
	v_add_f32_e32 v38, v0, v38
	v_xor_b32_e32 v0, 1, v244
	v_cmp_lt_i32_e32 vcc, v0, v36
	s_nop 1
	v_cndmask_b32_e32 v0, v244, v0, vcc
	v_lshlrev_b32_e32 v70, 2, v0
	ds_bpermute_b32 v39, v70, v38
	v_lshlrev_b32_e32 v0, 2, v42
	v_cmp_eq_u32_e32 vcc, 0, v40
	v_lshlrev_b32_e32 v40, 7, v136
	v_lshl_add_u32 v69, v0, 2, v40
	s_and_saveexec_b64 s[0:1], vcc
	s_cbranch_execz .LBB0_1163
	s_waitcnt lgkmcnt(0)
	v_add_f32_e32 v38, v38, v39
	ds_write_b32 v69, v38 offset:51712

.LBB0_1491:
	v_lshl_add_u64 v[206:207], v[38:39], 0, s[0:1]
	v_add_co_u32_e32 v208, vcc, s27, v206
	s_nop 1
	v_addc_co_u32_e32 v209, vcc, 0, v207, vcc
	v_lshl_add_u64 v[206:207], v[36:37], 0, s[0:1]
	v_add_co_u32_e32 v210, vcc, s27, v206
	s_nop 1
	v_addc_co_u32_e32 v211, vcc, 0, v207, vcc
	global_load_dwordx4 v[140:143], v[208:209], off
	global_load_dwordx4 v[144:147], v[210:211], off
	global_load_dwordx4 v[148:151], v[208:209], off offset:32
	global_load_dwordx4 v[152:155], v[210:211], off offset:32
	global_load_dwordx4 v[156:159], v[208:209], off offset:64
	global_load_dwordx4 v[160:163], v[210:211], off offset:64
	global_load_dwordx4 v[164:167], v[208:209], off offset:96
	global_load_dwordx4 v[168:171], v[210:211], off offset:96
	global_load_dwordx4 v[172:175], v[208:209], off offset:128
	global_load_dwordx4 v[176:179], v[210:211], off offset:128
	global_load_dwordx4 v[180:183], v[208:209], off offset:160
	global_load_dwordx4 v[184:187], v[210:211], off offset:160
	global_load_dwordx4 v[188:191], v[208:209], off offset:192
	global_load_dwordx4 v[192:195], v[210:211], off offset:192
	global_load_dwordx4 v[196:199], v[208:209], off offset:224
	global_load_dwordx4 v[200:203], v[210:211], off offset:224
	ds_read_b128 v[44:47], v42
	ds_read_b128 v[48:51], v42 offset:32
	ds_read_b128 v[52:55], v42 offset:64
	ds_read_b128 v[56:59], v42 offset:96
	ds_read_b128 v[60:63], v42 offset:128
	ds_read_b128 v[66:69], v42 offset:160
	ds_read_b128 v[70:73], v42 offset:192
	ds_read_b128 v[74:77], v42 offset:224
	v_add_u32_e32 v42, 0x100, v42
	s_add_u32 s0, s0, 0x100
	s_addc_u32 s1, s1, 0
	s_waitcnt vmcnt(14) lgkmcnt(7)
	v_mfma_f32_32x32x16_bf16 v[16:31], v[44:47], v[140:143], v[16:31]
	v_mfma_f32_32x32x16_bf16 v[0:15], v[44:47], v[144:147], v[0:15]
	s_waitcnt vmcnt(12) lgkmcnt(6)
	v_mfma_f32_32x32x16_bf16 v[16:31], v[48:51], v[148:151], v[16:31]
	v_mfma_f32_32x32x16_bf16 v[0:15], v[48:51], v[152:155], v[0:15]
	s_waitcnt vmcnt(10) lgkmcnt(5)
	v_mfma_f32_32x32x16_bf16 v[16:31], v[52:55], v[156:159], v[16:31]
	v_mfma_f32_32x32x16_bf16 v[0:15], v[52:55], v[160:163], v[0:15]
	s_waitcnt vmcnt(8) lgkmcnt(4)
	v_mfma_f32_32x32x16_bf16 v[16:31], v[56:59], v[164:167], v[16:31]
	v_mfma_f32_32x32x16_bf16 v[0:15], v[56:59], v[168:171], v[0:15]
	s_waitcnt vmcnt(6) lgkmcnt(3)
	v_mfma_f32_32x32x16_bf16 v[16:31], v[60:63], v[172:175], v[16:31]
	v_mfma_f32_32x32x16_bf16 v[0:15], v[60:63], v[176:179], v[0:15]
	s_waitcnt vmcnt(4) lgkmcnt(2)
	v_mfma_f32_32x32x16_bf16 v[16:31], v[66:69], v[180:183], v[16:31]
	v_mfma_f32_32x32x16_bf16 v[0:15], v[66:69], v[184:187], v[0:15]
	s_waitcnt vmcnt(2) lgkmcnt(1)
	v_mfma_f32_32x32x16_bf16 v[16:31], v[70:73], v[188:191], v[16:31]
	v_mfma_f32_32x32x16_bf16 v[0:15], v[70:73], v[192:195], v[0:15]
	s_waitcnt vmcnt(0) lgkmcnt(0)
	v_mfma_f32_32x32x16_bf16 v[16:31], v[74:77], v[196:199], v[16:31]
	v_mfma_f32_32x32x16_bf16 v[0:15], v[74:77], v[200:203], v[0:15]
	s_cmpk_eq_i32 s0, 0x200
	s_cbranch_scc0 .LBB0_1491
	s_nop 7
	v_mul_f32_e32 v16, 0xbfb8aa3b, v16
	v_lshlrev_b32_e32 v36, 1, v40
	v_exp_f32_e32 v16, v16
	v_mul_f32_e32 v0, 0xbfb8aa3b, v0
	v_lshl_add_u32 v36, v64, 1, v36
	v_and_b32_e32 v37, 64, v244
	v_exp_f32_e32 v0, v0
	v_add_u32_e32 v38, 64, v37
	v_mad_u32_u24 v37, v41, s24, v36
	ds_read_u16 v39, v37 offset:34816
	v_add_f32_e32 v16, 1.0, v16
	ds_read_u16 v37, v37 offset:34880
	v_rcp_f32_e32 v16, v16
	v_add_f32_e32 v0, 1.0, v0
	v_rcp_f32_e32 v0, v0
	s_waitcnt lgkmcnt(1)
	v_lshlrev_b32_e32 v39, 16, v39
	v_mul_f32_e32 v67, v16, v39
	s_waitcnt lgkmcnt(0)
	v_lshlrev_b32_e32 v16, 16, v37
	v_mul_f32_e32 v66, v0, v16
	v_xor_b32_e32 v16, 16, v244
	v_cmp_lt_i32_e32 vcc, v16, v38
	v_mul_f32_e32 v0, v66, v66
	v_fmac_f32_e32 v0, v67, v67
	v_cndmask_b32_e32 v16, v244, v16, vcc
	v_lshlrev_b32_e32 v16, 2, v16
	ds_bpermute_b32 v37, v16, v0
	v_lshlrev_b32_e32 v39, 7, v136
	s_waitcnt lgkmcnt(0)
	v_add_f32_e32 v0, v0, v37
	v_xor_b32_e32 v37, 8, v244
	v_cmp_lt_i32_e32 vcc, v37, v38
	s_nop 1
	v_cndmask_b32_e32 v37, v244, v37, vcc
	v_lshlrev_b32_e32 v44, 2, v37
	ds_bpermute_b32 v37, v44, v0
	s_waitcnt lgkmcnt(0)
	v_add_f32_e32 v0, v0, v37
	v_xor_b32_e32 v37, 4, v244
	v_cmp_lt_i32_e32 vcc, v37, v38
	s_nop 1
	v_cndmask_b32_e32 v37, v244, v37, vcc
	v_lshlrev_b32_e32 v68, 2, v37
	ds_bpermute_b32 v37, v68, v0
	s_waitcnt lgkmcnt(0)
	v_add_f32_e32 v0, v0, v37
	v_xor_b32_e32 v37, 2, v244
	v_cmp_lt_i32_e32 vcc, v37, v38
	s_nop 1
	v_cndmask_b32_e32 v37, v244, v37, vcc
	v_lshlrev_b32_e32 v69, 2, v37
	ds_bpermute_b32 v37, v69, v0
	s_waitcnt lgkmcnt(0)
	v_add_f32_e32 v37, v0, v37
	v_xor_b32_e32 v0, 1, v244
	v_cmp_lt_i32_e32 vcc, v0, v38
	s_nop 1
	v_cndmask_b32_e32 v0, v244, v0, vcc
	v_lshlrev_b32_e32 v71, 2, v0
	ds_bpermute_b32 v38, v71, v37
	v_lshlrev_b32_e32 v0, 2, v41
	v_cmp_eq_u32_e32 vcc, 0, v40
	v_lshl_add_u32 v70, v0, 2, v39
	s_and_saveexec_b64 s[0:1], vcc
	s_cbranch_execz .LBB0_1494
	s_waitcnt lgkmcnt(0)
	v_add_f32_e32 v37, v37, v38
	ds_write_b32 v70, v37 offset:51712
